# v82 + write-through (sc0 sc1) on the 16-byte output stores of P2 and P10 (outputs consumed on other XCDs after a global barrier)
# speedup vs baseline: 1.0058x; 1.0005x over previous
.LBB0_289:
	s_lshl_b64 s[42:43], s[64:65], 13
	s_add_u32 s42, s62, s42
	s_waitcnt lgkmcnt(0)
	s_barrier
	ds_read_b128 v[0:3], v88 offset:38912
	s_addc_u32 s43, s63, s43
	v_lshl_add_u64 v[4:5], s[42:43], 0, v[28:29]
	v_add_co_u32_e32 v4, vcc, 0x15700000, v4
	s_add_i32 s96, s96, s52
	s_add_i32 s79, s79, s80
	s_add_i32 s95, s95, s52
	v_addc_co_u32_e32 v5, vcc, 0, v5, vcc
	s_cmpk_lt_i32 s96, 0x200
	s_waitcnt lgkmcnt(0)
	global_store_dwordx4 v[4:5], v[0:3], off sc0 sc1
	s_barrier
	s_cbranch_scc0 .LBB0_343

.LBB0_314:
	v_ashrrev_i32_e32 v3, 3, v2
	v_add_u32_e32 v5, 0x200, v2
	v_and_or_b32 v3, v3, -16, v19
	v_lshrrev_b32_e32 v4, 1, v2
	v_cmp_lt_i32_e32 vcc, s93, v2
	v_mov_b32_e32 v2, v5
	v_lshl_add_u32 v5, v3, 2, 0
	v_lshlrev_b32_e32 v3, 1, v3
	v_and_b32_e32 v4, 56, v4
	v_sub_u32_e32 v3, v5, v3
	v_add_u32_e32 v6, 0x197f0, v5
	v_mad_u32_u24 v5, v4, s75, v5
	v_mad_u32_u24 v3, v4, s78, v3
	ds_read_b32 v4, v5 offset:38912
	ds_read_b32 v7, v5 offset:39952
	ds_read_b32 v8, v5 offset:40992
	ds_read_b32 v9, v5 offset:42032
	ds_read_b32 v10, v5 offset:43072
	ds_read_b32 v11, v5 offset:44112
	ds_read_b32 v12, v5 offset:45152
	ds_read_b32 v5, v5 offset:46192
	ds_read_b32 v6, v6
	ds_read_u16 v13, v3
	ds_read_u16 v14, v3 offset:528
	ds_read_u16 v15, v3 offset:1056
	ds_read_u16 v31, v3 offset:1584
	ds_read_u16 v93, v3 offset:2112
	ds_read_u16 v94, v3 offset:2640
	ds_read_u16 v95, v3 offset:3168
	ds_read_u16 v3, v3 offset:3696
	s_waitcnt lgkmcnt(8)
	v_sub_f32_e32 v4, v6, v4
	v_sub_f32_e32 v7, v6, v7
	v_sub_f32_e32 v8, v6, v8
	v_sub_f32_e32 v9, v6, v9
	v_sub_f32_e32 v10, v6, v10
	v_sub_f32_e32 v11, v6, v11
	v_sub_f32_e32 v12, v6, v12
	v_sub_f32_e32 v5, v6, v5
	v_mul_f32_e32 v4, 0x3fb8aa3b, v4
	v_mul_f32_e32 v7, 0x3fb8aa3b, v7
	v_mul_f32_e32 v8, 0x3fb8aa3b, v8
	v_mul_f32_e32 v9, 0x3fb8aa3b, v9
	v_mul_f32_e32 v10, 0x3fb8aa3b, v10
	v_mul_f32_e32 v11, 0x3fb8aa3b, v11
	v_mul_f32_e32 v12, 0x3fb8aa3b, v12
	v_mul_f32_e32 v5, 0x3fb8aa3b, v5
	v_exp_f32_e32 v4, v4
	v_exp_f32_e32 v7, v7
	v_exp_f32_e32 v8, v8
	v_exp_f32_e32 v9, v9
	v_exp_f32_e32 v10, v10
	v_exp_f32_e32 v11, v11
	v_exp_f32_e32 v12, v12
	v_exp_f32_e32 v5, v5
	s_waitcnt lgkmcnt(7)
	v_lshlrev_b32_e32 v6, 16, v13
	s_waitcnt lgkmcnt(6)
	v_lshlrev_b32_e32 v13, 16, v14
	s_waitcnt lgkmcnt(5)
	v_lshlrev_b32_e32 v14, 16, v15
	s_waitcnt lgkmcnt(4)
	v_lshlrev_b32_e32 v15, 16, v31
	s_waitcnt lgkmcnt(3)
	v_lshlrev_b32_e32 v31, 16, v93
	s_waitcnt lgkmcnt(2)
	v_lshlrev_b32_e32 v93, 16, v94
	s_waitcnt lgkmcnt(1)
	v_lshlrev_b32_e32 v94, 16, v95
	s_waitcnt lgkmcnt(0)
	v_lshlrev_b32_e32 v3, 16, v3
	v_mul_f32_e32 v4, v4, v6
	v_mul_f32_e32 v6, v7, v13
	v_mul_f32_e32 v7, v8, v14
	s_or_b64 s[66:67], vcc, s[66:67]
	v_mul_f32_e32 v8, v9, v15
	v_mul_f32_e32 v9, v10, v31
	v_mul_f32_e32 v10, v11, v93
	v_mul_f32_e32 v11, v12, v94
	v_mul_f32_e32 v3, v5, v3
	v_cvt_pk_bf16_f32 v4, v4, v6
	v_cvt_pk_bf16_f32 v5, v7, v8
	v_cvt_pk_bf16_f32 v6, v9, v10
	v_cvt_pk_bf16_f32 v7, v11, v3
	global_store_dwordx4 v[0:1], v[4:7], off sc0 sc1
	v_lshl_add_u64 v[0:1], v[0:1], 0, s[60:61]
	s_andn2_b64 exec, exec, s[66:67]
	s_cbranch_execnz .LBB0_314

.LBB0_322:
	v_lshrrev_b32_e32 v3, 2, v2
	v_ashrrev_i32_e32 v4, 3, v2
	v_and_or_b32 v5, v3, 48, v19
	v_and_b32_e32 v3, 12, v3
	v_and_or_b32 v3, v4, s94, v3
	v_mul_u32_u24_e32 v5, 0x210, v5
	v_lshlrev_b32_e32 v3, 1, v3
	v_add3_u32 v3, s77, v5, v3
	ds_read2_b64 v[4:7], v3 offset1:4
	v_add_u32_e32 v8, 0x200, v2
	v_cmp_lt_i32_e32 vcc, s93, v2
	s_or_b64 s[42:43], vcc, s[42:43]
	v_mov_b32_e32 v2, v8
	s_waitcnt lgkmcnt(0)
	global_store_dwordx4 v[0:1], v[4:7], off sc0 sc1
	v_lshl_add_u64 v[0:1], v[0:1], 0, s[60:61]
	s_andn2_b64 exec, exec, s[42:43]
	s_cbranch_execnz .LBB0_322

.LBB0_346:
	s_lshl_b64 s[42:43], s[64:65], 13
	s_add_u32 s42, s62, s42
	s_addc_u32 s43, s63, s43
	s_waitcnt lgkmcnt(0)
	s_barrier
	ds_read_b128 v[0:3], v88 offset:38912
	v_lshl_add_u64 v[4:5], s[42:43], 0, v[26:27]
	v_add_co_u32_e32 v4, vcc, 0x15700000, v4
	s_movk_i32 s33, 0x100
	s_nop 0
	v_addc_co_u32_e32 v5, vcc, 0, v5, vcc
	s_mov_b64 s[64:65], 0
	s_and_b64 vcc, exec, s[66:67]
	s_waitcnt lgkmcnt(0)
	global_store_dwordx4 v[4:5], v[0:3], off sc0 sc1
	s_barrier
	s_cbranch_vccnz .LBB0_400

.LBB0_371:
	v_ashrrev_i32_e32 v4, 3, v1
	v_add_u32_e32 v6, 0x200, v1
	v_and_or_b32 v4, v4, -16, v21
	v_lshrrev_b32_e32 v5, 1, v1
	v_cmp_lt_i32_e32 vcc, s96, v1
	v_mov_b32_e32 v1, v6
	v_lshl_add_u32 v6, v4, 2, 0
	v_lshlrev_b32_e32 v4, 1, v4
	v_and_b32_e32 v5, 56, v5
	v_sub_u32_e32 v4, v6, v4
	v_add_u32_e32 v7, 0x197f0, v6
	v_mad_u32_u24 v6, v5, s79, v6
	v_mad_u32_u24 v4, v5, s82, v4
	ds_read_b32 v5, v6 offset:38912
	ds_read_b32 v8, v6 offset:39952
	ds_read_b32 v9, v6 offset:40992
	ds_read_b32 v10, v6 offset:42032
	ds_read_b32 v11, v6 offset:43072
	ds_read_b32 v12, v6 offset:44112
	ds_read_b32 v13, v6 offset:45152
	ds_read_b32 v6, v6 offset:46192
	ds_read_b32 v7, v7
	ds_read_u16 v14, v4
	ds_read_u16 v15, v4 offset:528
	ds_read_u16 v29, v4 offset:1056
	ds_read_u16 v93, v4 offset:1584
	ds_read_u16 v94, v4 offset:2112
	ds_read_u16 v95, v4 offset:2640
	ds_read_u16 v96, v4 offset:3168
	ds_read_u16 v4, v4 offset:3696
	s_waitcnt lgkmcnt(8)
	v_sub_f32_e32 v5, v7, v5
	v_sub_f32_e32 v8, v7, v8
	v_sub_f32_e32 v9, v7, v9
	v_sub_f32_e32 v10, v7, v10
	v_sub_f32_e32 v11, v7, v11
	v_sub_f32_e32 v12, v7, v12
	v_sub_f32_e32 v13, v7, v13
	v_sub_f32_e32 v6, v7, v6
	v_mul_f32_e32 v5, 0x3fb8aa3b, v5
	v_mul_f32_e32 v8, 0x3fb8aa3b, v8
	v_mul_f32_e32 v9, 0x3fb8aa3b, v9
	v_mul_f32_e32 v10, 0x3fb8aa3b, v10
	v_mul_f32_e32 v11, 0x3fb8aa3b, v11
	v_mul_f32_e32 v12, 0x3fb8aa3b, v12
	v_mul_f32_e32 v13, 0x3fb8aa3b, v13
	v_mul_f32_e32 v6, 0x3fb8aa3b, v6
	v_exp_f32_e32 v5, v5
	v_exp_f32_e32 v8, v8
	v_exp_f32_e32 v9, v9
	v_exp_f32_e32 v10, v10
	v_exp_f32_e32 v11, v11
	v_exp_f32_e32 v12, v12
	v_exp_f32_e32 v13, v13
	v_exp_f32_e32 v6, v6
	s_waitcnt lgkmcnt(7)
	v_lshlrev_b32_e32 v7, 16, v14
	s_waitcnt lgkmcnt(6)
	v_lshlrev_b32_e32 v14, 16, v15
	s_waitcnt lgkmcnt(5)
	v_lshlrev_b32_e32 v15, 16, v29
	s_waitcnt lgkmcnt(4)
	v_lshlrev_b32_e32 v29, 16, v93
	s_waitcnt lgkmcnt(3)
	v_lshlrev_b32_e32 v93, 16, v94
	s_waitcnt lgkmcnt(2)
	v_lshlrev_b32_e32 v94, 16, v95
	s_waitcnt lgkmcnt(1)
	v_lshlrev_b32_e32 v95, 16, v96
	s_waitcnt lgkmcnt(0)
	v_lshlrev_b32_e32 v4, 16, v4
	v_mul_f32_e32 v5, v5, v7
	v_mul_f32_e32 v7, v8, v14
	s_or_b64 s[64:65], vcc, s[64:65]
	v_mul_f32_e32 v8, v9, v15
	v_mul_f32_e32 v9, v10, v29
	v_mul_f32_e32 v10, v11, v93
	v_mul_f32_e32 v11, v12, v94
	v_mul_f32_e32 v12, v13, v95
	v_mul_f32_e32 v13, v6, v4
	v_cvt_pk_bf16_f32 v4, v5, v7
	v_cvt_pk_bf16_f32 v5, v8, v9
	v_cvt_pk_bf16_f32 v6, v10, v11
	v_cvt_pk_bf16_f32 v7, v12, v13
	global_store_dwordx4 v[2:3], v[4:7], off sc0 sc1
	v_lshl_add_u64 v[2:3], v[2:3], 0, s[60:61]
	s_andn2_b64 exec, exec, s[64:65]
	s_cbranch_execnz .LBB0_371

.LBB0_379:
	v_lshrrev_b32_e32 v3, 2, v2
	v_ashrrev_i32_e32 v4, 3, v2
	v_and_or_b32 v5, v3, 48, v21
	v_and_b32_e32 v3, 12, v3
	v_and_or_b32 v3, v4, s97, v3
	v_mul_u32_u24_e32 v5, 0x210, v5
	v_lshlrev_b32_e32 v3, 1, v3
	v_add3_u32 v3, s81, v5, v3
	ds_read2_b64 v[4:7], v3 offset1:4
	v_add_u32_e32 v8, 0x200, v2
	v_cmp_lt_i32_e32 vcc, s96, v2
	s_or_b64 s[50:51], vcc, s[50:51]
	v_mov_b32_e32 v2, v8
	s_waitcnt lgkmcnt(0)
	global_store_dwordx4 v[0:1], v[4:7], off sc0 sc1
	v_lshl_add_u64 v[0:1], v[0:1], 0, s[60:61]
	s_andn2_b64 exec, exec, s[50:51]
	s_cbranch_execnz .LBB0_379

.LBB0_1274:
	s_nop 0
	v_mov_b64_e32 v[146:147], s[12:13]
	v_lshl_or_b32 v148, s9, 8, v154
	v_mad_i64_i32 v[160:161], s[8:9], v144, s61, v[146:147]
	v_or_b32_e32 v162, 16, v144
	v_ashrrev_i32_e32 v149, 31, v148
	v_lshlrev_b64 v[148:149], 1, v[148:149]
	v_lshl_add_u64 v[160:161], v[160:161], 0, v[148:149]
	s_waitcnt vmcnt(7)
	v_mov_b32_e32 v145, v172
	v_fmamk_f32 v145, v145, 0x3a000000, v158
	v_mul_f32_e32 v163, 0x4f800000, v145
	v_cmp_gt_f32_e32 vcc, s62, v145
	s_nop 1
	v_cndmask_b32_e32 v145, v145, v163, vcc
	v_sqrt_f32_e32 v164, v145
	v_ashrrev_i32_e32 v163, 31, v162
	v_add_u32_e32 v165, -1, v164
	v_add_u32_e32 v166, 1, v164
	v_fma_f32 v167, -v165, v164, v145
	v_fma_f32 v168, -v166, v164, v145
	v_cmp_ge_f32_e64 s[8:9], 0, v167
	s_nop 1
	v_cndmask_b32_e64 v164, v164, v165, s[8:9]
	v_cmp_lt_f32_e64 s[8:9], 0, v168
	s_nop 1
	v_cndmask_b32_e64 v164, v164, v166, s[8:9]
	v_mul_f32_e32 v165, 0x37800000, v164
	v_cndmask_b32_e32 v164, v164, v165, vcc
	v_cmp_class_f32_e32 vcc, v145, v159
	s_nop 1
	v_cndmask_b32_e32 v145, v164, v145, vcc
	v_div_scale_f32 v166, s[8:9], v145, v145, 1.0
	v_rcp_f32_e32 v167, v166
	v_lshl_add_u64 v[164:165], v[162:163], 2, s[16:17]
	v_div_scale_f32 v163, vcc, 1.0, v145, 1.0
	v_fma_f32 v168, -v166, v167, 1.0
	v_fmac_f32_e32 v167, v168, v167
	v_mul_f32_e32 v168, v163, v167
	v_fma_f32 v169, -v166, v168, v163
	v_fmac_f32_e32 v168, v169, v167
	v_fma_f32 v163, -v166, v168, v163
	v_div_fmas_f32 v163, v163, v167, v168
	v_div_fixup_f32 v166, v163, v145, 1.0
	v_pk_mul_f32 v[126:127], v[126:127], v[166:167] op_sel_hi:[1,0]
	v_pk_mul_f32 v[124:125], v[124:125], v[166:167] op_sel_hi:[1,0]
	v_pk_mul_f32 v[122:123], v[122:123], v[166:167] op_sel_hi:[1,0]
	v_pk_mul_f32 v[120:121], v[120:121], v[166:167] op_sel_hi:[1,0]
	v_pk_mul_f32 v[118:119], v[118:119], v[166:167] op_sel_hi:[1,0]
	v_pk_mul_f32 v[116:117], v[116:117], v[166:167] op_sel_hi:[1,0]
	v_pk_mul_f32 v[168:169], v[114:115], v[166:167] op_sel_hi:[1,0]
	v_pk_mul_f32 v[166:167], v[112:113], v[166:167] op_sel_hi:[1,0]
	v_cvt_pk_bf16_f32 v112, v124, v125
	v_cvt_pk_bf16_f32 v113, v126, v127
	v_cvt_pk_bf16_f32 v114, v120, v121
	v_cvt_pk_bf16_f32 v115, v122, v123
	global_store_dwordx4 v[160:161], v[112:115], off sc0 sc1
	s_nop 1
	v_cvt_pk_bf16_f32 v112, v116, v117
	v_cvt_pk_bf16_f32 v113, v118, v119
	v_cvt_pk_bf16_f32 v114, v166, v167
	v_cvt_pk_bf16_f32 v115, v168, v169
	global_store_dwordx4 v[160:161], v[112:115], off offset:256 sc0 sc1
	s_nop 0
	s_nop 0
	v_or_b32_e32 v112, 32, v144
	s_waitcnt vmcnt(7)
	v_mov_b32_e32 v113, v173
	v_fmamk_f32 v113, v113, 0x3a000000, v158
	v_mul_f32_e32 v114, 0x4f800000, v113
	v_cmp_gt_f32_e32 vcc, s62, v113
	s_nop 1
	v_cndmask_b32_e32 v116, v113, v114, vcc
	v_sqrt_f32_e32 v117, v116
	v_mad_i64_i32 v[114:115], s[8:9], v162, s61, v[146:147]
	v_ashrrev_i32_e32 v113, 31, v112
	v_add_u32_e32 v118, -1, v117
	v_add_u32_e32 v119, 1, v117
	v_fma_f32 v120, -v118, v117, v116
	v_fma_f32 v121, -v119, v117, v116
	v_cmp_ge_f32_e64 s[8:9], 0, v120
	v_lshl_add_u64 v[114:115], v[114:115], 0, v[148:149]
	s_nop 0
	v_cndmask_b32_e64 v117, v117, v118, s[8:9]
	v_cmp_lt_f32_e64 s[8:9], 0, v121
	s_nop 1
	v_cndmask_b32_e64 v117, v117, v119, s[8:9]
	v_mul_f32_e32 v118, 0x37800000, v117
	v_cndmask_b32_e32 v117, v117, v118, vcc
	v_cmp_class_f32_e32 vcc, v116, v159
	s_nop 1
	v_cndmask_b32_e32 v118, v117, v116, vcc
	v_div_scale_f32 v119, s[8:9], v118, v118, 1.0
	v_rcp_f32_e32 v120, v119
	v_lshl_add_u64 v[116:117], v[112:113], 2, s[16:17]
	v_div_scale_f32 v113, vcc, 1.0, v118, 1.0
	v_fma_f32 v121, -v119, v120, 1.0
	v_fmac_f32_e32 v120, v121, v120
	v_mul_f32_e32 v121, v113, v120
	v_fma_f32 v122, -v119, v121, v113
	v_fmac_f32_e32 v121, v122, v120
	v_fma_f32 v113, -v119, v121, v113
	v_div_fmas_f32 v113, v113, v120, v121
	v_div_fixup_f32 v118, v113, v118, 1.0
	v_pk_mul_f32 v[110:111], v[110:111], v[118:119] op_sel_hi:[1,0]
	v_pk_mul_f32 v[108:109], v[108:109], v[118:119] op_sel_hi:[1,0]
	v_pk_mul_f32 v[106:107], v[106:107], v[118:119] op_sel_hi:[1,0]
	v_pk_mul_f32 v[104:105], v[104:105], v[118:119] op_sel_hi:[1,0]
	v_pk_mul_f32 v[102:103], v[102:103], v[118:119] op_sel_hi:[1,0]
	v_pk_mul_f32 v[100:101], v[100:101], v[118:119] op_sel_hi:[1,0]
	v_pk_mul_f32 v[120:121], v[98:99], v[118:119] op_sel_hi:[1,0]
	v_pk_mul_f32 v[118:119], v[96:97], v[118:119] op_sel_hi:[1,0]
	v_cvt_pk_bf16_f32 v96, v108, v109
	v_cvt_pk_bf16_f32 v97, v110, v111
	v_cvt_pk_bf16_f32 v98, v104, v105
	v_cvt_pk_bf16_f32 v99, v106, v107
	global_store_dwordx4 v[114:115], v[96:99], off sc0 sc1
	s_nop 1
	v_cvt_pk_bf16_f32 v96, v100, v101
	v_cvt_pk_bf16_f32 v97, v102, v103
	v_cvt_pk_bf16_f32 v98, v118, v119
	v_cvt_pk_bf16_f32 v99, v120, v121
	global_store_dwordx4 v[114:115], v[96:99], off offset:256 sc0 sc1
	s_nop 0
	s_nop 0
	v_or_b32_e32 v96, 48, v144
	s_waitcnt vmcnt(7)
	v_mov_b32_e32 v97, v174
	v_fmamk_f32 v97, v97, 0x3a000000, v158
	v_mul_f32_e32 v98, 0x4f800000, v97
	v_cmp_gt_f32_e32 vcc, s62, v97
	s_nop 1
	v_cndmask_b32_e32 v100, v97, v98, vcc
	v_sqrt_f32_e32 v101, v100
	v_mad_i64_i32 v[98:99], s[8:9], v112, s61, v[146:147]
	v_ashrrev_i32_e32 v97, 31, v96
	v_add_u32_e32 v102, -1, v101
	v_add_u32_e32 v103, 1, v101
	v_fma_f32 v104, -v102, v101, v100
	v_fma_f32 v105, -v103, v101, v100
	v_cmp_ge_f32_e64 s[8:9], 0, v104
	v_lshl_add_u64 v[98:99], v[98:99], 0, v[148:149]
	s_nop 0
	v_cndmask_b32_e64 v101, v101, v102, s[8:9]
	v_cmp_lt_f32_e64 s[8:9], 0, v105
	s_nop 1
	v_cndmask_b32_e64 v101, v101, v103, s[8:9]
	v_mul_f32_e32 v102, 0x37800000, v101
	v_cndmask_b32_e32 v101, v101, v102, vcc
	v_cmp_class_f32_e32 vcc, v100, v159
	s_nop 1
	v_cndmask_b32_e32 v102, v101, v100, vcc
	v_div_scale_f32 v103, s[8:9], v102, v102, 1.0
	v_rcp_f32_e32 v104, v103
	v_lshl_add_u64 v[100:101], v[96:97], 2, s[16:17]
	v_div_scale_f32 v97, vcc, 1.0, v102, 1.0
	v_fma_f32 v105, -v103, v104, 1.0
	v_fmac_f32_e32 v104, v105, v104
	v_mul_f32_e32 v105, v97, v104
	v_fma_f32 v106, -v103, v105, v97
	v_fmac_f32_e32 v105, v106, v104
	v_fma_f32 v97, -v103, v105, v97
	v_div_fmas_f32 v97, v97, v104, v105
	v_div_fixup_f32 v102, v97, v102, 1.0
	v_pk_mul_f32 v[94:95], v[94:95], v[102:103] op_sel_hi:[1,0]
	v_pk_mul_f32 v[92:93], v[92:93], v[102:103] op_sel_hi:[1,0]
	v_pk_mul_f32 v[90:91], v[90:91], v[102:103] op_sel_hi:[1,0]
	v_pk_mul_f32 v[88:89], v[88:89], v[102:103] op_sel_hi:[1,0]
	v_pk_mul_f32 v[86:87], v[86:87], v[102:103] op_sel_hi:[1,0]
	v_pk_mul_f32 v[84:85], v[84:85], v[102:103] op_sel_hi:[1,0]
	v_pk_mul_f32 v[104:105], v[82:83], v[102:103] op_sel_hi:[1,0]
	v_pk_mul_f32 v[102:103], v[80:81], v[102:103] op_sel_hi:[1,0]
	v_cvt_pk_bf16_f32 v80, v92, v93
	v_cvt_pk_bf16_f32 v81, v94, v95
	v_cvt_pk_bf16_f32 v82, v88, v89
	v_cvt_pk_bf16_f32 v83, v90, v91
	global_store_dwordx4 v[98:99], v[80:83], off sc0 sc1
	s_nop 1
	v_cvt_pk_bf16_f32 v80, v84, v85
	v_cvt_pk_bf16_f32 v81, v86, v87
	v_cvt_pk_bf16_f32 v82, v102, v103
	v_cvt_pk_bf16_f32 v83, v104, v105
	global_store_dwordx4 v[98:99], v[80:83], off offset:256 sc0 sc1
	s_nop 0
	s_waitcnt vmcnt(7)
	v_mov_b32_e32 v80, v175
	v_fmamk_f32 v80, v80, 0x3a000000, v158
	v_mul_f32_e32 v81, 0x4f800000, v80
	v_cmp_gt_f32_e32 vcc, s62, v80
	s_nop 1
	v_cndmask_b32_e32 v82, v80, v81, vcc
	v_sqrt_f32_e32 v83, v82
	v_mad_i64_i32 v[80:81], s[8:9], v96, s61, v[146:147]
	v_lshl_add_u64 v[80:81], v[80:81], 0, v[148:149]
	v_add_u32_e32 v84, -1, v83
	v_add_u32_e32 v85, 1, v83
	v_fma_f32 v86, -v84, v83, v82
	v_fma_f32 v87, -v85, v83, v82
	v_cmp_ge_f32_e64 s[8:9], 0, v86
	s_nop 1
	v_cndmask_b32_e64 v83, v83, v84, s[8:9]
	v_cmp_lt_f32_e64 s[8:9], 0, v87
	s_nop 1
	v_cndmask_b32_e64 v83, v83, v85, s[8:9]
	v_mul_f32_e32 v84, 0x37800000, v83
	v_cndmask_b32_e32 v83, v83, v84, vcc
	v_cmp_class_f32_e32 vcc, v82, v159
	s_nop 1
	v_cndmask_b32_e32 v82, v83, v82, vcc
	v_div_scale_f32 v83, s[8:9], v82, v82, 1.0
	v_rcp_f32_e32 v84, v83
	v_div_scale_f32 v85, vcc, 1.0, v82, 1.0
	v_fma_f32 v86, -v83, v84, 1.0
	v_fmac_f32_e32 v84, v86, v84
	v_mul_f32_e32 v86, v85, v84
	v_fma_f32 v87, -v83, v86, v85
	v_fmac_f32_e32 v86, v87, v84
	v_fma_f32 v83, -v83, v86, v85
	v_div_fmas_f32 v83, v83, v84, v86
	v_div_fixup_f32 v82, v83, v82, 1.0
	v_pk_mul_f32 v[78:79], v[78:79], v[82:83] op_sel_hi:[1,0]
	v_pk_mul_f32 v[76:77], v[76:77], v[82:83] op_sel_hi:[1,0]
	v_pk_mul_f32 v[74:75], v[74:75], v[82:83] op_sel_hi:[1,0]
	v_pk_mul_f32 v[72:73], v[72:73], v[82:83] op_sel_hi:[1,0]
	v_pk_mul_f32 v[70:71], v[70:71], v[82:83] op_sel_hi:[1,0]
	v_pk_mul_f32 v[68:69], v[68:69], v[82:83] op_sel_hi:[1,0]
	v_pk_mul_f32 v[84:85], v[66:67], v[82:83] op_sel_hi:[1,0]
	v_pk_mul_f32 v[82:83], v[64:65], v[82:83] op_sel_hi:[1,0]
	v_cvt_pk_bf16_f32 v64, v76, v77
	v_cvt_pk_bf16_f32 v65, v78, v79
	v_cvt_pk_bf16_f32 v66, v72, v73
	v_cvt_pk_bf16_f32 v67, v74, v75
	global_store_dwordx4 v[80:81], v[64:67], off sc0 sc1
	s_nop 1
	v_cvt_pk_bf16_f32 v64, v68, v69
	v_cvt_pk_bf16_f32 v65, v70, v71
	v_cvt_pk_bf16_f32 v66, v82, v83
	v_cvt_pk_bf16_f32 v67, v84, v85
	global_store_dwordx4 v[80:81], v[64:67], off offset:256 sc0 sc1
	s_nop 0
	s_waitcnt vmcnt(7)
	v_mov_b32_e32 v64, v176
	v_fmamk_f32 v64, v64, 0x3a000000, v158
	v_mul_f32_e32 v65, 0x4f800000, v64
	v_cmp_gt_f32_e32 vcc, s62, v64
	s_nop 1
	v_cndmask_b32_e32 v66, v64, v65, vcc
	v_sqrt_f32_e32 v67, v66
	v_add_u32_e32 v64, 0x80, v144
	v_mad_i64_i32 v[64:65], s[8:9], v64, s61, v[146:147]
	v_add_u32_e32 v68, -1, v67
	v_add_u32_e32 v69, 1, v67
	v_fma_f32 v70, -v68, v67, v66
	v_fma_f32 v71, -v69, v67, v66
	v_cmp_ge_f32_e64 s[8:9], 0, v70
	v_lshl_add_u64 v[64:65], v[64:65], 0, v[148:149]
	s_nop 0
	v_cndmask_b32_e64 v67, v67, v68, s[8:9]
	v_cmp_lt_f32_e64 s[8:9], 0, v71
	s_nop 1
	v_cndmask_b32_e64 v67, v67, v69, s[8:9]
	v_mul_f32_e32 v68, 0x37800000, v67
	v_cndmask_b32_e32 v67, v67, v68, vcc
	v_cmp_class_f32_e32 vcc, v66, v159
	s_nop 1
	v_cndmask_b32_e32 v66, v67, v66, vcc
	v_div_scale_f32 v67, s[8:9], v66, v66, 1.0
	v_rcp_f32_e32 v68, v67
	v_div_scale_f32 v69, vcc, 1.0, v66, 1.0
	v_fma_f32 v70, -v67, v68, 1.0
	v_fmac_f32_e32 v68, v70, v68
	v_mul_f32_e32 v70, v69, v68
	v_fma_f32 v71, -v67, v70, v69
	v_fmac_f32_e32 v70, v71, v68
	v_fma_f32 v67, -v67, v70, v69
	v_div_fmas_f32 v67, v67, v68, v70
	v_div_fixup_f32 v66, v67, v66, 1.0
	v_pk_mul_f32 v[62:63], v[62:63], v[66:67] op_sel_hi:[1,0]
	v_pk_mul_f32 v[60:61], v[60:61], v[66:67] op_sel_hi:[1,0]
	v_pk_mul_f32 v[58:59], v[58:59], v[66:67] op_sel_hi:[1,0]
	v_pk_mul_f32 v[56:57], v[56:57], v[66:67] op_sel_hi:[1,0]
	v_pk_mul_f32 v[54:55], v[54:55], v[66:67] op_sel_hi:[1,0]
	v_pk_mul_f32 v[52:53], v[52:53], v[66:67] op_sel_hi:[1,0]
	v_pk_mul_f32 v[68:69], v[50:51], v[66:67] op_sel_hi:[1,0]
	v_pk_mul_f32 v[66:67], v[48:49], v[66:67] op_sel_hi:[1,0]
	v_cvt_pk_bf16_f32 v48, v60, v61
	v_cvt_pk_bf16_f32 v49, v62, v63
	v_cvt_pk_bf16_f32 v50, v56, v57
	v_cvt_pk_bf16_f32 v51, v58, v59
	global_store_dwordx4 v[64:65], v[48:51], off sc0 sc1
	s_nop 1
	v_cvt_pk_bf16_f32 v48, v52, v53
	v_cvt_pk_bf16_f32 v49, v54, v55
	v_cvt_pk_bf16_f32 v50, v66, v67
	v_cvt_pk_bf16_f32 v51, v68, v69
	global_store_dwordx4 v[64:65], v[48:51], off offset:256 sc0 sc1
	s_nop 0
	s_waitcnt vmcnt(7)
	v_mov_b32_e32 v48, v177
	v_fmamk_f32 v48, v48, 0x3a000000, v158
	v_mul_f32_e32 v49, 0x4f800000, v48
	v_cmp_gt_f32_e32 vcc, s62, v48
	s_nop 1
	v_cndmask_b32_e32 v50, v48, v49, vcc
	v_sqrt_f32_e32 v51, v50
	v_add_u32_e32 v48, 0x90, v144
	v_mad_i64_i32 v[48:49], s[8:9], v48, s61, v[146:147]
	v_add_u32_e32 v52, -1, v51
	v_add_u32_e32 v53, 1, v51
	v_fma_f32 v54, -v52, v51, v50
	v_fma_f32 v55, -v53, v51, v50
	v_cmp_ge_f32_e64 s[8:9], 0, v54
	v_lshl_add_u64 v[48:49], v[48:49], 0, v[148:149]
	s_nop 0
	v_cndmask_b32_e64 v51, v51, v52, s[8:9]
	v_cmp_lt_f32_e64 s[8:9], 0, v55
	s_nop 1
	v_cndmask_b32_e64 v51, v51, v53, s[8:9]
	v_mul_f32_e32 v52, 0x37800000, v51
	v_cndmask_b32_e32 v51, v51, v52, vcc
	v_cmp_class_f32_e32 vcc, v50, v159
	s_nop 1
	v_cndmask_b32_e32 v50, v51, v50, vcc
	v_div_scale_f32 v51, s[8:9], v50, v50, 1.0
	v_rcp_f32_e32 v52, v51
	v_div_scale_f32 v53, vcc, 1.0, v50, 1.0
	v_fma_f32 v54, -v51, v52, 1.0
	v_fmac_f32_e32 v52, v54, v52
	v_mul_f32_e32 v54, v53, v52
	v_fma_f32 v55, -v51, v54, v53
	v_fmac_f32_e32 v54, v55, v52
	v_fma_f32 v51, -v51, v54, v53
	v_div_fmas_f32 v51, v51, v52, v54
	v_div_fixup_f32 v50, v51, v50, 1.0
	v_pk_mul_f32 v[46:47], v[46:47], v[50:51] op_sel_hi:[1,0]
	v_pk_mul_f32 v[44:45], v[44:45], v[50:51] op_sel_hi:[1,0]
	v_pk_mul_f32 v[42:43], v[42:43], v[50:51] op_sel_hi:[1,0]
	v_pk_mul_f32 v[40:41], v[40:41], v[50:51] op_sel_hi:[1,0]
	v_pk_mul_f32 v[38:39], v[38:39], v[50:51] op_sel_hi:[1,0]
	v_pk_mul_f32 v[36:37], v[36:37], v[50:51] op_sel_hi:[1,0]
	v_pk_mul_f32 v[52:53], v[34:35], v[50:51] op_sel_hi:[1,0]
	v_pk_mul_f32 v[50:51], v[32:33], v[50:51] op_sel_hi:[1,0]
	v_cvt_pk_bf16_f32 v32, v44, v45
	v_cvt_pk_bf16_f32 v33, v46, v47
	v_cvt_pk_bf16_f32 v34, v40, v41
	v_cvt_pk_bf16_f32 v35, v42, v43
	global_store_dwordx4 v[48:49], v[32:35], off sc0 sc1
	s_nop 1
	v_cvt_pk_bf16_f32 v32, v36, v37
	v_cvt_pk_bf16_f32 v33, v38, v39
	v_cvt_pk_bf16_f32 v34, v50, v51
	v_cvt_pk_bf16_f32 v35, v52, v53
	global_store_dwordx4 v[48:49], v[32:35], off offset:256 sc0 sc1
	s_nop 0
	s_waitcnt vmcnt(7)
	v_mov_b32_e32 v32, v178
	v_fmamk_f32 v32, v32, 0x3a000000, v158
	v_mul_f32_e32 v33, 0x4f800000, v32
	v_cmp_gt_f32_e32 vcc, s62, v32
	s_nop 1
	v_cndmask_b32_e32 v34, v32, v33, vcc
	v_sqrt_f32_e32 v35, v34
	v_add_u32_e32 v32, 0xa0, v144
	v_mad_i64_i32 v[32:33], s[8:9], v32, s61, v[146:147]
	v_add_u32_e32 v36, -1, v35
	v_add_u32_e32 v37, 1, v35
	v_fma_f32 v38, -v36, v35, v34
	v_fma_f32 v39, -v37, v35, v34
	v_cmp_ge_f32_e64 s[8:9], 0, v38
	v_lshl_add_u64 v[32:33], v[32:33], 0, v[148:149]
	s_nop 0
	v_cndmask_b32_e64 v35, v35, v36, s[8:9]
	v_cmp_lt_f32_e64 s[8:9], 0, v39
	s_nop 1
	v_cndmask_b32_e64 v35, v35, v37, s[8:9]
	v_mul_f32_e32 v36, 0x37800000, v35
	v_cndmask_b32_e32 v35, v35, v36, vcc
	v_cmp_class_f32_e32 vcc, v34, v159
	s_nop 1
	v_cndmask_b32_e32 v34, v35, v34, vcc
	v_div_scale_f32 v35, s[8:9], v34, v34, 1.0
	v_rcp_f32_e32 v36, v35
	v_div_scale_f32 v37, vcc, 1.0, v34, 1.0
	v_fma_f32 v38, -v35, v36, 1.0
	v_fmac_f32_e32 v36, v38, v36
	v_mul_f32_e32 v38, v37, v36
	v_fma_f32 v39, -v35, v38, v37
	v_fmac_f32_e32 v38, v39, v36
	v_fma_f32 v35, -v35, v38, v37
	v_div_fmas_f32 v35, v35, v36, v38
	v_div_fixup_f32 v34, v35, v34, 1.0
	v_pk_mul_f32 v[30:31], v[30:31], v[34:35] op_sel_hi:[1,0]
	v_pk_mul_f32 v[28:29], v[28:29], v[34:35] op_sel_hi:[1,0]
	v_pk_mul_f32 v[26:27], v[26:27], v[34:35] op_sel_hi:[1,0]
	v_pk_mul_f32 v[24:25], v[24:25], v[34:35] op_sel_hi:[1,0]
	v_pk_mul_f32 v[22:23], v[22:23], v[34:35] op_sel_hi:[1,0]
	v_pk_mul_f32 v[20:21], v[20:21], v[34:35] op_sel_hi:[1,0]
	v_pk_mul_f32 v[36:37], v[18:19], v[34:35] op_sel_hi:[1,0]
	v_pk_mul_f32 v[34:35], v[16:17], v[34:35] op_sel_hi:[1,0]
	v_cvt_pk_bf16_f32 v16, v28, v29
	v_cvt_pk_bf16_f32 v17, v30, v31
	v_cvt_pk_bf16_f32 v18, v24, v25
	v_cvt_pk_bf16_f32 v19, v26, v27
	global_store_dwordx4 v[32:33], v[16:19], off sc0 sc1
	s_nop 1
	v_cvt_pk_bf16_f32 v16, v20, v21
	v_cvt_pk_bf16_f32 v17, v22, v23
	v_cvt_pk_bf16_f32 v18, v34, v35
	v_cvt_pk_bf16_f32 v19, v36, v37
	global_store_dwordx4 v[32:33], v[16:19], off offset:256 sc0 sc1
	s_nop 0
	s_nop 0
	v_add_u32_e32 v17, 0xb0, v144
	s_waitcnt vmcnt(7)
	v_mov_b32_e32 v16, v179
	v_fmamk_f32 v16, v16, 0x3a000000, v158
	v_mul_f32_e32 v18, 0x4f800000, v16
	v_cmp_gt_f32_e32 vcc, s62, v16
	s_nop 1
	v_cndmask_b32_e32 v18, v16, v18, vcc
	v_sqrt_f32_e32 v19, v18
	v_mad_i64_i32 v[16:17], s[8:9], v17, s61, v[146:147]
	v_lshl_add_u64 v[16:17], v[16:17], 0, v[148:149]
	v_add_u32_e32 v20, -1, v19
	v_add_u32_e32 v21, 1, v19
	v_fma_f32 v22, -v20, v19, v18
	v_fma_f32 v23, -v21, v19, v18
	v_cmp_ge_f32_e64 s[8:9], 0, v22
	s_nop 1
	v_cndmask_b32_e64 v19, v19, v20, s[8:9]
	v_cmp_lt_f32_e64 s[8:9], 0, v23
	s_nop 1
	v_cndmask_b32_e64 v19, v19, v21, s[8:9]
	v_mul_f32_e32 v20, 0x37800000, v19
	v_cndmask_b32_e32 v19, v19, v20, vcc
	v_cmp_class_f32_e32 vcc, v18, v159
	s_nop 1
	v_cndmask_b32_e32 v18, v19, v18, vcc
	v_div_scale_f32 v19, s[8:9], v18, v18, 1.0
	v_rcp_f32_e32 v20, v19
	v_div_scale_f32 v21, vcc, 1.0, v18, 1.0
	v_fma_f32 v22, -v19, v20, 1.0
	v_fmac_f32_e32 v20, v22, v20
	v_mul_f32_e32 v22, v21, v20
	v_fma_f32 v23, -v19, v22, v21
	v_fmac_f32_e32 v22, v23, v20
	v_fma_f32 v19, -v19, v22, v21
	v_div_fmas_f32 v19, v19, v20, v22
	v_div_fixup_f32 v18, v19, v18, 1.0
	s_andn2_b64 vcc, exec, s[6:7]
	v_pk_mul_f32 v[14:15], v[14:15], v[18:19] op_sel_hi:[1,0]
	v_pk_mul_f32 v[12:13], v[12:13], v[18:19] op_sel_hi:[1,0]
	v_pk_mul_f32 v[10:11], v[10:11], v[18:19] op_sel_hi:[1,0]
	v_pk_mul_f32 v[8:9], v[8:9], v[18:19] op_sel_hi:[1,0]
	v_pk_mul_f32 v[6:7], v[6:7], v[18:19] op_sel_hi:[1,0]
	v_pk_mul_f32 v[4:5], v[4:5], v[18:19] op_sel_hi:[1,0]
	v_pk_mul_f32 v[20:21], v[2:3], v[18:19] op_sel_hi:[1,0]
	v_pk_mul_f32 v[18:19], v[0:1], v[18:19] op_sel_hi:[1,0]
	v_cvt_pk_bf16_f32 v0, v12, v13
	v_cvt_pk_bf16_f32 v1, v14, v15
	v_cvt_pk_bf16_f32 v2, v8, v9
	v_cvt_pk_bf16_f32 v3, v10, v11
	s_mov_b64 s[6:7], -1
	global_store_dwordx4 v[16:17], v[0:3], off sc0 sc1
	s_nop 1
	v_cvt_pk_bf16_f32 v0, v4, v5
	v_cvt_pk_bf16_f32 v1, v6, v7
	v_cvt_pk_bf16_f32 v2, v18, v19
	v_cvt_pk_bf16_f32 v3, v20, v21
	global_store_dwordx4 v[16:17], v[0:3], off offset:256 sc0 sc1
	s_cbranch_vccnz .LBB0_1267
	s_andn2_b64 vcc, exec, s[10:11]
	s_cbranch_vccnz .LBB0_1266
	s_barrier
	s_branch .LBB0_1266
